# weight-conversion loops: counted waits (vmcnt(32) before item a, vmcnt(4) before item b) so item a's transpose/pack/store overlaps item b's loads landing
# speedup vs baseline: 1.0076x; 1.0076x over previous
; #define LAS __attribute__((address_space(3)))
; __device__ __forceinline__ unsigned pk2(float lo, float hi) { const f32x2 v = {lo, hi}; const bf16x2_cv b = __builtin_convertvector(v, bf16x2_cv); return __builtin_bit_cast(unsigned, b); }
; #define LAS __attribute__((address_space(3)))
; __device__ __forceinline__ unsigned f2bf(float f) { unsigned u = __builtin_bit_cast(unsigned, f); return (u + 0x7fffu + ((u >> 16) & 1u)) >> 16; }
; __device__ __forceinline__ unsigned pk2(float lo, float hi) { return f2bf(lo) | (f2bf(hi) << 16); }
; __device__ __forceinline__ void conv_store(const ConvItem& c, const float (&wv)[32], LAS float* scr, int lane) {
;     const int nblk = c.N / 32, kb = c.item / nblk, nb = c.item % nblk, k0 = 64 * kb, n0 = 32 * nb;
;     int r0 = n0;
;     if (c.gu) { const int up = n0 >= DFF ? 1 : 0, nn = n0 - up * DFF; r0 = (nn >> 7) * 256 + up * 128 + (nn & 127); }
; #pragma unroll
;     for (int i = 0; i < 32; ++i) scr[(2 * i + (lane >> 5)) * 33 + (lane & 31)] = wv[i];
;     asm volatile("s_waitcnt lgkmcnt(0)" ::: "memory");
;     const int cc = lane & 7;
; #pragma unroll
;     for (int j = 0; j < 4; ++j) { const int n = (lane >> 3) + 8 * j; const LAS float* sp = scr + (8 * cc) * 33 + n;
;         v4u o; o.x = pk2(sp[0 * 33], sp[1 * 33]); o.y = pk2(sp[2 * 33], sp[3 * 33]); o.z = pk2(sp[4 * 33], sp[5 * 33]); o.w = pk2(sp[6 * 33], sp[7 * 33]);
;         *(v4u*)(c.WT + (size_t)(r0 + n) * c.K + k0 + 8 * cc) = o; }
;     asm volatile("s_waitcnt lgkmcnt(0)" ::: "memory");
; }
.LBB0_776:
	s_waitcnt vmcnt(4)
	ds_write2_b32 v8, v9, v10 offset1:66
	ds_write2_b32 v8, v11, v12 offset0:132 offset1:198
	ds_write2_b32 v16, v13, v14 offset0:8 offset1:74
	ds_write2_b32 v16, v15, v18 offset0:140 offset1:206
	ds_write2_b32 v17, v20, v21 offset0:16 offset1:82
	ds_write2_b32 v17, v23, v24 offset0:148 offset1:214
	ds_write2_b32 v19, v25, v27 offset0:24 offset1:90
	ds_write2_b32 v19, v28, v29 offset0:156 offset1:222
	ds_write2_b32 v22, v31, v32 offset0:32 offset1:98
	ds_write2_b32 v22, v33, v34 offset0:164 offset1:230
	ds_write2_b32 v26, v35, v36 offset0:40 offset1:106
	ds_write2_b32 v26, v37, v38 offset0:172 offset1:238
	ds_write2_b32 v30, v39, v40 offset0:48 offset1:114
	ds_write2_b32 v30, v41, v42 offset0:180 offset1:246
	ds_write2_b32 v47, v43, v44 offset0:56 offset1:122
	ds_write2_b32 v47, v45, v46 offset0:188 offset1:254
	s_waitcnt lgkmcnt(0)
	ds_read2_b32 v[14:15], v4 offset1:8
	ds_read2_b32 v[16:17], v4 offset0:33 offset1:41
	ds_read2_b32 v[18:19], v4 offset0:66 offset1:74
	ds_read2_b32 v[20:21], v4 offset0:99 offset1:107
	ds_read2_b32 v[22:23], v4 offset0:132 offset1:140
	s_waitcnt lgkmcnt(4)
	v_bfe_u32 v1, v14, 16, 1
	v_add3_u32 v1, v14, v1, s46
	s_waitcnt lgkmcnt(3)
	v_bfe_u32 v9, v16, 16, 1
	v_lshrrev_b32_e32 v1, 16, v1
	v_add3_u32 v9, v16, v9, s46
	ds_read2_b32 v[24:25], v4 offset0:165 offset1:173
	v_and_or_b32 v10, v9, s33, v1
	s_waitcnt lgkmcnt(3)
	v_bfe_u32 v1, v18, 16, 1
	v_add3_u32 v1, v18, v1, s46
	s_waitcnt lgkmcnt(2)
	v_bfe_u32 v9, v20, 16, 1
	ds_read2_b32 v[26:27], v4 offset0:198 offset1:206
	v_lshrrev_b32_e32 v1, 16, v1
	v_add3_u32 v9, v20, v9, s46
	ds_read2_b32 v[28:29], v4 offset0:231 offset1:239
	v_and_or_b32 v11, v9, s33, v1
	s_waitcnt lgkmcnt(3)
	v_bfe_u32 v1, v22, 16, 1
	v_add3_u32 v1, v22, v1, s46
	s_waitcnt lgkmcnt(2)
	v_bfe_u32 v9, v24, 16, 1
	v_lshrrev_b32_e32 v1, 16, v1
	v_add3_u32 v9, v24, v9, s46
	v_and_or_b32 v12, v9, s33, v1
	s_waitcnt lgkmcnt(1)
	v_bfe_u32 v1, v26, 16, 1
	v_add3_u32 v1, v26, v1, s46
	s_waitcnt lgkmcnt(0)
	v_bfe_u32 v9, v28, 16, 1
	v_lshrrev_b32_e32 v1, 16, v1
	v_add3_u32 v9, v28, v9, s46
	v_and_or_b32 v13, v9, s33, v1
	v_add_u32_e32 v1, s56, v3
	v_ashrrev_i32_e32 v9, 31, v1
	v_mul_lo_u32 v9, s82, v9
	v_mul_lo_u32 v14, s83, v1
	v_mad_u64_u32 v[30:31], s[4:5], s82, v1, 0
	v_add3_u32 v31, v31, v9, v14
	v_lshl_add_u64 v[30:31], v[30:31], 1, s[84:85]
	s_lshl_b64 s[4:5], s[90:91], 1
	v_lshl_add_u64 v[30:31], v[30:31], 0, s[4:5]
	v_mov_b32_e32 v1, v161
	v_lshl_add_u64 v[30:31], v[30:31], 0, v[0:1]
	v_bfe_u32 v9, v15, 16, 1
	global_store_dwordx4 v[30:31], v[10:13], off
	v_add3_u32 v9, v15, v9, s46
	v_lshrrev_b32_e32 v9, 16, v9
	v_bfe_u32 v10, v17, 16, 1
	v_add3_u32 v10, v17, v10, s46
	v_and_or_b32 v10, v10, s33, v9
	v_bfe_u32 v9, v19, 16, 1
	v_add3_u32 v9, v19, v9, s46
	v_bfe_u32 v11, v21, 16, 1
	v_lshrrev_b32_e32 v9, 16, v9
	v_add3_u32 v11, v21, v11, s46
	v_and_or_b32 v11, v11, s33, v9
	v_bfe_u32 v9, v23, 16, 1
	v_add3_u32 v9, v23, v9, s46
	v_bfe_u32 v12, v25, 16, 1
	v_lshrrev_b32_e32 v9, 16, v9
	v_add3_u32 v12, v25, v12, s46
	v_and_or_b32 v12, v12, s33, v9
	v_bfe_u32 v9, v27, 16, 1
	v_add3_u32 v9, v27, v9, s46
	v_bfe_u32 v13, v29, 16, 1
	v_lshrrev_b32_e32 v9, 16, v9
	v_add3_u32 v13, v29, v13, s46
	v_and_or_b32 v13, v13, s33, v9
	v_add_u32_e32 v9, s56, v5
	v_ashrrev_i32_e32 v14, 31, v9
	v_mul_lo_u32 v16, s82, v14
	v_mul_lo_u32 v17, s83, v9
	v_mad_u64_u32 v[14:15], s[52:53], s82, v9, 0
	v_add3_u32 v15, v15, v16, v17
	v_lshl_add_u64 v[14:15], v[14:15], 1, s[84:85]
	v_lshl_add_u64 v[14:15], v[14:15], 0, s[4:5]
	ds_read2_b32 v[16:17], v4 offset0:16 offset1:24
	v_lshl_add_u64 v[14:15], v[14:15], 0, v[0:1]
	global_store_dwordx4 v[14:15], v[10:13], off
	ds_read2_b32 v[14:15], v4 offset0:49 offset1:57
	ds_read2_b32 v[18:19], v4 offset0:82 offset1:90
	ds_read2_b32 v[20:21], v4 offset0:115 offset1:123
	s_waitcnt lgkmcnt(3)
	v_bfe_u32 v9, v16, 16, 1
	v_add3_u32 v9, v16, v9, s46
	s_waitcnt lgkmcnt(2)
	v_bfe_u32 v10, v14, 16, 1
	ds_read2_b32 v[22:23], v4 offset0:148 offset1:156
	v_lshrrev_b32_e32 v9, 16, v9
	v_add3_u32 v10, v14, v10, s46
	ds_read2_b32 v[24:25], v4 offset0:181 offset1:189
	v_and_or_b32 v10, v10, s33, v9
	s_waitcnt lgkmcnt(3)
	v_bfe_u32 v9, v18, 16, 1
	v_add3_u32 v9, v18, v9, s46
	s_waitcnt lgkmcnt(2)
	v_bfe_u32 v11, v20, 16, 1
	ds_read2_b32 v[26:27], v4 offset0:214 offset1:222
	v_lshrrev_b32_e32 v9, 16, v9
	v_add3_u32 v11, v20, v11, s46
	ds_read2_b32 v[28:29], v4 offset0:247 offset1:255
	v_and_or_b32 v11, v11, s33, v9
	s_waitcnt lgkmcnt(3)
	v_bfe_u32 v9, v22, 16, 1
	v_add3_u32 v9, v22, v9, s46
	s_waitcnt lgkmcnt(2)
	v_bfe_u32 v12, v24, 16, 1
	v_lshrrev_b32_e32 v9, 16, v9
	v_add3_u32 v12, v24, v12, s46
	v_and_or_b32 v12, v12, s33, v9
	s_waitcnt lgkmcnt(1)
	v_bfe_u32 v9, v26, 16, 1
	v_add3_u32 v9, v26, v9, s46
	s_waitcnt lgkmcnt(0)
	v_bfe_u32 v13, v28, 16, 1
	v_lshrrev_b32_e32 v9, 16, v9
	v_add3_u32 v13, v28, v13, s46
	v_and_or_b32 v13, v13, s33, v9
	v_add_u32_e32 v9, s56, v6
	v_ashrrev_i32_e32 v14, 31, v9
	v_mul_lo_u32 v14, s82, v14
	v_mul_lo_u32 v16, s83, v9
	v_mad_u64_u32 v[30:31], s[52:53], s82, v9, 0
	v_add3_u32 v31, v31, v14, v16
	v_lshl_add_u64 v[30:31], v[30:31], 1, s[84:85]
	v_lshl_add_u64 v[30:31], v[30:31], 0, s[4:5]
	v_lshl_add_u64 v[30:31], v[30:31], 0, v[0:1]
	v_bfe_u32 v9, v17, 16, 1
	global_store_dwordx4 v[30:31], v[10:13], off
	v_add3_u32 v9, v17, v9, s46
	v_lshrrev_b32_e32 v9, 16, v9
	v_bfe_u32 v10, v15, 16, 1
	v_add3_u32 v10, v15, v10, s46
	v_and_or_b32 v10, v10, s33, v9
	v_bfe_u32 v9, v19, 16, 1
	v_add3_u32 v9, v19, v9, s46
	v_bfe_u32 v11, v21, 16, 1
	v_lshrrev_b32_e32 v9, 16, v9
	v_add3_u32 v11, v21, v11, s46
	v_and_or_b32 v11, v11, s33, v9
	v_bfe_u32 v9, v23, 16, 1
	v_add3_u32 v9, v23, v9, s46
	v_bfe_u32 v12, v25, 16, 1
	v_lshrrev_b32_e32 v9, 16, v9
	v_add3_u32 v12, v25, v12, s46
	v_and_or_b32 v12, v12, s33, v9
	v_bfe_u32 v9, v27, 16, 1
	v_add3_u32 v9, v27, v9, s46
	v_bfe_u32 v13, v29, 16, 1
	v_lshrrev_b32_e32 v9, 16, v9
	v_add3_u32 v13, v29, v13, s46
	v_and_or_b32 v13, v13, s33, v9
	v_add_u32_e32 v9, s56, v7
	v_ashrrev_i32_e32 v14, 31, v9
	v_mul_lo_u32 v16, s82, v14
	v_mul_lo_u32 v17, s83, v9
	v_mad_u64_u32 v[14:15], s[52:53], s82, v9, 0
	v_add3_u32 v15, v15, v16, v17
	v_lshl_add_u64 v[14:15], v[14:15], 1, s[84:85]
	v_lshl_add_u64 v[14:15], v[14:15], 0, s[4:5]
	v_lshl_add_u64 v[14:15], v[14:15], 0, v[0:1]
	global_store_dwordx4 v[14:15], v[10:13], off
	s_waitcnt lgkmcnt(0)

; #define LAS __attribute__((address_space(3)))
; __device__ __forceinline__ unsigned pk2(float lo, float hi) { const f32x2 v = {lo, hi}; const bf16x2_cv b = __builtin_convertvector(v, bf16x2_cv); return __builtin_bit_cast(unsigned, b); }
; #define LAS __attribute__((address_space(3)))
; __device__ __forceinline__ unsigned pk2(float lo, float hi) { return f2bf(lo) | (f2bf(hi) << 16); }
; __device__ __forceinline__ void conv_store(const ConvItem& c, const float (&wv)[32], LAS float* scr, int lane) {
;     ...
;     for (int i = 0; i < 32; ++i) scr[(2 * i + (lane >> 5)) * 33 + (lane & 31)] = wv[i];
;     asm volatile("s_waitcnt lgkmcnt(0)" ::: "memory");
;     const int cc = lane & 7;
; #pragma unroll
;     for (int j = 0; j < 4; ++j) { const int n = (lane >> 3) + 8 * j; const LAS float* sp = scr + (8 * cc) * 33 + n;
;         v4u o; o.x = pk2(sp[0 * 33], sp[1 * 33]); o.y = pk2(sp[2 * 33], sp[3 * 33]); o.z = pk2(sp[4 * 33], sp[5 * 33]); o.w = pk2(sp[6 * 33], sp[7 * 33]);
;         *(v4u*)(c.WT + (size_t)(r0 + n) * c.K + k0 + 8 * cc) = o; }
;     asm volatile("s_waitcnt lgkmcnt(0)" ::: "memory");
.LBB0_836:
	s_waitcnt vmcnt(32)
	ds_write2_b32 v8, v1, v16 offset1:66
	ds_write2_b32 v8, v17, v19 offset0:132 offset1:198
	v_add_u32_e32 v16, 0x400, v8
	ds_write2_b32 v16, v22, v26 offset0:8 offset1:74
	ds_write2_b32 v16, v30, v47 offset0:140 offset1:206
	v_add_u32_e32 v17, 0x800, v8
	v_add_u32_e32 v19, 0xc00, v8
	v_add_u32_e32 v22, 0x1000, v8
	v_add_u32_e32 v26, 0x1400, v8
	v_add_u32_e32 v30, 0x1800, v8
	v_add_u32_e32 v47, 0x1c00, v8
	ds_write2_b32 v17, v48, v49 offset0:16 offset1:82
	ds_write2_b32 v17, v50, v51 offset0:148 offset1:214
	ds_write2_b32 v19, v52, v53 offset0:24 offset1:90
	ds_write2_b32 v19, v54, v55 offset0:156 offset1:222
	ds_write2_b32 v22, v56, v57 offset0:32 offset1:98
	ds_write2_b32 v22, v58, v59 offset0:164 offset1:230
	ds_write2_b32 v26, v60, v61 offset0:40 offset1:106
	ds_write2_b32 v26, v62, v63 offset0:172 offset1:238
	ds_write2_b32 v30, v64, v65 offset0:48 offset1:114
	ds_write2_b32 v30, v66, v67 offset0:180 offset1:246
	ds_write2_b32 v47, v68, v69 offset0:56 offset1:122
	ds_write2_b32 v47, v70, v71 offset0:188 offset1:254
	s_waitcnt lgkmcnt(0)
	ds_read2_b32 v[52:53], v4 offset1:8
	ds_read2_b32 v[54:55], v4 offset0:33 offset1:41
	ds_read2_b32 v[56:57], v4 offset0:66 offset1:74
	ds_read2_b32 v[58:59], v4 offset0:99 offset1:107
	ds_read2_b32 v[60:61], v4 offset0:132 offset1:140
	s_waitcnt lgkmcnt(4)
	v_bfe_u32 v1, v52, 16, 1
	v_add3_u32 v1, v52, v1, s46
	s_waitcnt lgkmcnt(3)
	v_bfe_u32 v48, v54, 16, 1
	v_lshrrev_b32_e32 v1, 16, v1
	v_add3_u32 v48, v54, v48, s46
	ds_read2_b32 v[62:63], v4 offset0:165 offset1:173
	v_and_or_b32 v48, v48, s33, v1
	s_waitcnt lgkmcnt(3)
	v_bfe_u32 v1, v56, 16, 1
	v_add3_u32 v1, v56, v1, s46
	s_waitcnt lgkmcnt(2)
	v_bfe_u32 v49, v58, 16, 1
	ds_read2_b32 v[64:65], v4 offset0:198 offset1:206
	v_lshrrev_b32_e32 v1, 16, v1
	v_add3_u32 v49, v58, v49, s46
	ds_read2_b32 v[66:67], v4 offset0:231 offset1:239
	v_and_or_b32 v49, v49, s33, v1
	s_waitcnt lgkmcnt(3)
	v_bfe_u32 v1, v60, 16, 1
	v_add3_u32 v1, v60, v1, s46
	s_waitcnt lgkmcnt(2)
	v_bfe_u32 v50, v62, 16, 1
	v_lshrrev_b32_e32 v1, 16, v1
	v_add3_u32 v50, v62, v50, s46
	v_and_or_b32 v50, v50, s33, v1
	s_waitcnt lgkmcnt(1)
	v_bfe_u32 v1, v64, 16, 1
	v_add3_u32 v1, v64, v1, s46
	s_waitcnt lgkmcnt(0)
	v_bfe_u32 v51, v66, 16, 1
	v_lshrrev_b32_e32 v1, 16, v1
	v_add3_u32 v51, v66, v51, s46
	v_and_or_b32 v51, v51, s33, v1
	v_add_u32_e32 v1, s92, v3
	v_ashrrev_i32_e32 v52, 31, v1
	v_mul_lo_u32 v52, s78, v52
	v_mul_lo_u32 v54, s79, v1
	v_mad_u64_u32 v[68:69], s[4:5], s78, v1, 0
	v_add3_u32 v69, v69, v52, v54
	v_lshl_add_u64 v[68:69], v[68:69], 1, s[80:81]
	s_lshl_b64 s[4:5], s[52:53], 1
	v_lshl_add_u64 v[68:69], v[68:69], 0, s[4:5]
	v_mov_b32_e32 v1, v161
	v_lshl_add_u64 v[68:69], v[68:69], 0, v[0:1]
	global_store_dwordx4 v[68:69], v[48:51], off
	v_bfe_u32 v52, v67, 16, 1
	v_add3_u32 v52, v67, v52, s46
	v_bfe_u32 v48, v53, 16, 1
	v_add3_u32 v48, v53, v48, s46
	v_bfe_u32 v49, v55, 16, 1
	v_lshrrev_b32_e32 v48, 16, v48
	v_add3_u32 v49, v55, v49, s46
	v_and_or_b32 v48, v49, s33, v48
	v_bfe_u32 v49, v57, 16, 1
	v_add3_u32 v49, v57, v49, s46
	v_bfe_u32 v50, v59, 16, 1
	v_lshrrev_b32_e32 v49, 16, v49
	v_add3_u32 v50, v59, v50, s46
	v_and_or_b32 v49, v50, s33, v49
	v_bfe_u32 v50, v61, 16, 1
	v_add3_u32 v50, v61, v50, s46
	v_bfe_u32 v51, v63, 16, 1
	v_lshrrev_b32_e32 v50, 16, v50
	v_add3_u32 v51, v63, v51, s46
	v_and_or_b32 v50, v51, s33, v50
	v_bfe_u32 v51, v65, 16, 1
	v_add3_u32 v51, v65, v51, s46
	v_lshrrev_b32_e32 v51, 16, v51
	v_and_or_b32 v51, v52, s33, v51
	v_add_u32_e32 v52, s92, v5
	v_ashrrev_i32_e32 v53, 31, v52
	v_mul_lo_u32 v54, s78, v53
	v_mul_lo_u32 v55, s79, v52
	v_mad_u64_u32 v[52:53], s[52:53], s78, v52, 0
	v_add3_u32 v53, v53, v54, v55
	v_lshl_add_u64 v[52:53], v[52:53], 1, s[80:81]
	v_lshl_add_u64 v[52:53], v[52:53], 0, s[4:5]
	ds_read2_b32 v[54:55], v4 offset0:16 offset1:24
	v_lshl_add_u64 v[52:53], v[52:53], 0, v[0:1]
	global_store_dwordx4 v[52:53], v[48:51], off
	ds_read2_b32 v[52:53], v4 offset0:49 offset1:57
	ds_read2_b32 v[56:57], v4 offset0:82 offset1:90
	ds_read2_b32 v[58:59], v4 offset0:115 offset1:123
	s_waitcnt lgkmcnt(3)
	v_bfe_u32 v48, v54, 16, 1
	v_add3_u32 v48, v54, v48, s46
	s_waitcnt lgkmcnt(2)
	v_bfe_u32 v49, v52, 16, 1
	ds_read2_b32 v[60:61], v4 offset0:148 offset1:156
	v_lshrrev_b32_e32 v48, 16, v48
	v_add3_u32 v49, v52, v49, s46
	ds_read2_b32 v[62:63], v4 offset0:181 offset1:189
	v_and_or_b32 v48, v49, s33, v48
	s_waitcnt lgkmcnt(3)
	v_bfe_u32 v49, v56, 16, 1
	v_add3_u32 v49, v56, v49, s46
	s_waitcnt lgkmcnt(2)
	v_bfe_u32 v50, v58, 16, 1
	ds_read2_b32 v[64:65], v4 offset0:214 offset1:222
	v_lshrrev_b32_e32 v49, 16, v49
	v_add3_u32 v50, v58, v50, s46
	ds_read2_b32 v[66:67], v4 offset0:247 offset1:255
	v_and_or_b32 v49, v50, s33, v49
	s_waitcnt lgkmcnt(3)
	v_bfe_u32 v50, v60, 16, 1
	v_add3_u32 v50, v60, v50, s46
	s_waitcnt lgkmcnt(2)
	v_bfe_u32 v51, v62, 16, 1
	v_lshrrev_b32_e32 v50, 16, v50
	v_add3_u32 v51, v62, v51, s46
	v_and_or_b32 v50, v51, s33, v50
	s_waitcnt lgkmcnt(1)
	v_bfe_u32 v51, v64, 16, 1
	v_add3_u32 v51, v64, v51, s46
	s_waitcnt lgkmcnt(0)
	v_bfe_u32 v52, v66, 16, 1
	v_lshrrev_b32_e32 v51, 16, v51
	v_add3_u32 v52, v66, v52, s46
	v_and_or_b32 v51, v52, s33, v51
	v_add_u32_e32 v52, s92, v6
	v_ashrrev_i32_e32 v54, 31, v52
	v_mul_lo_u32 v54, s78, v54
	v_mul_lo_u32 v56, s79, v52
	v_mad_u64_u32 v[68:69], s[52:53], s78, v52, 0
	v_add3_u32 v69, v69, v54, v56
	v_lshl_add_u64 v[68:69], v[68:69], 1, s[80:81]
	v_lshl_add_u64 v[68:69], v[68:69], 0, s[4:5]
	v_lshl_add_u64 v[68:69], v[68:69], 0, v[0:1]
	global_store_dwordx4 v[68:69], v[48:51], off
	v_bfe_u32 v52, v67, 16, 1
	v_add3_u32 v52, v67, v52, s46
	v_bfe_u32 v48, v55, 16, 1
	v_add3_u32 v48, v55, v48, s46
	v_bfe_u32 v49, v53, 16, 1
	v_lshrrev_b32_e32 v48, 16, v48
	v_add3_u32 v49, v53, v49, s46
	v_and_or_b32 v48, v49, s33, v48
	v_bfe_u32 v49, v57, 16, 1
	v_add3_u32 v49, v57, v49, s46
	v_bfe_u32 v50, v59, 16, 1
	v_lshrrev_b32_e32 v49, 16, v49
	v_add3_u32 v50, v59, v50, s46
	v_and_or_b32 v49, v50, s33, v49
	v_bfe_u32 v50, v61, 16, 1
	v_add3_u32 v50, v61, v50, s46
	v_bfe_u32 v51, v63, 16, 1
	v_lshrrev_b32_e32 v50, 16, v50
	v_add3_u32 v51, v63, v51, s46
	v_and_or_b32 v50, v51, s33, v50
	v_bfe_u32 v51, v65, 16, 1
	v_add3_u32 v51, v65, v51, s46
	v_lshrrev_b32_e32 v51, 16, v51
	v_and_or_b32 v51, v52, s33, v51
	v_add_u32_e32 v52, s92, v7
	v_ashrrev_i32_e32 v53, 31, v52
	v_mul_lo_u32 v54, s78, v53
	v_mul_lo_u32 v55, s79, v52
	v_mad_u64_u32 v[52:53], s[52:53], s78, v52, 0
	v_add3_u32 v53, v53, v54, v55
	v_lshl_add_u64 v[52:53], v[52:53], 1, s[80:81]
	v_lshl_add_u64 v[52:53], v[52:53], 0, s[4:5]
	v_lshl_add_u64 v[52:53], v[52:53], 0, v[0:1]
	global_store_dwordx4 v[52:53], v[48:51], off
	s_waitcnt lgkmcnt(0)
	s_andn2_b64 vcc, exec, s[86:87]
	s_cbranch_vccnz .Lc1_drain
; __device__ __forceinline__ void conv_store(const ConvItem& c, const float (&wv)[32], LAS float* scr, int lane) {
;     const int nblk = c.N / 32, kb = c.item / nblk, nb = c.item % nblk, k0 = 64 * kb, n0 = 32 * nb;
;     int r0 = n0;
;     if (c.gu) { const int up = n0 >= DFF ? 1 : 0, nn = n0 - up * DFF; r0 = (nn >> 7) * 256 + up * 128 + (nn & 127); }
; __device__ __forceinline__ void convert_weights(KP Pp, int layer, LAS unsigned char* lds, int gw, int ngw, int wave, int lane) {
;     ...
;         if (two) conv_store(b, wb, scr, lane);
	s_xor_b64 s[4:5], s[88:89], -1
	s_andn2_b64 vcc, exec, s[4:5]
	s_cbranch_vccnz .LBB0_776
	s_cmpk_gt_i32 s24, 0xaf
	s_cselect_b32 s4, 0xffffea00, 0
	s_cselect_b32 s5, 0x80, 0
	s_add_i32 s4, s4, s56
	s_lshl_b32 s4, s4, 1
	s_and_b32 s24, s56, 0x60
	s_and_b32 s4, s4, 0xffffff00
	s_or_b32 s5, s24, s5
	s_or_b32 s56, s5, s4
	s_branch .LBB0_776
.Lc1_drain:
	s_waitcnt vmcnt(0)
	s_branch .LBB0_777

; #define LAS __attribute__((address_space(3)))
; __device__ __forceinline__ unsigned pk2(float lo, float hi) { const f32x2 v = {lo, hi}; const bf16x2_cv b = __builtin_convertvector(v, bf16x2_cv); return __builtin_bit_cast(unsigned, b); }
; #define LAS __attribute__((address_space(3)))
; __device__ __forceinline__ unsigned pk2(float lo, float hi) { return f2bf(lo) | (f2bf(hi) << 16); }
; __device__ __forceinline__ void conv_store(const ConvItem& c, const float (&wv)[32], LAS float* scr, int lane) {
;     ...
; #pragma unroll
;     for (int i = 0; i < 32; ++i) scr[(2 * i + (lane >> 5)) * 33 + (lane & 31)] = wv[i];
;     asm volatile("s_waitcnt lgkmcnt(0)" ::: "memory");
;     const int cc = lane & 7;
; #pragma unroll
;     for (int j = 0; j < 4; ++j) { const int n = (lane >> 3) + 8 * j; const LAS float* sp = scr + (8 * cc) * 33 + n;
;         v4u o; o.x = pk2(sp[0 * 33], sp[1 * 33]); o.y = pk2(sp[2 * 33], sp[3 * 33]); o.z = pk2(sp[4 * 33], sp[5 * 33]); o.w = pk2(sp[6 * 33], sp[7 * 33]);
;         *(v4u*)(c.WT + (size_t)(r0 + n) * c.K + k0 + 8 * cc) = o; }
;     asm volatile("s_waitcnt lgkmcnt(0)" ::: "memory");
.LBB0_874:
	s_waitcnt vmcnt(4)
	ds_write2_b32 v8, v9, v10 offset1:66
	ds_write2_b32 v8, v11, v12 offset0:132 offset1:198
	ds_write2_b32 v41, v13, v14 offset0:8 offset1:74
	ds_write2_b32 v41, v15, v16 offset0:140 offset1:206
	ds_write2_b32 v42, v17, v18 offset0:16 offset1:82
	ds_write2_b32 v42, v19, v20 offset0:148 offset1:214
	ds_write2_b32 v43, v21, v22 offset0:24 offset1:90
	ds_write2_b32 v43, v23, v24 offset0:156 offset1:222
	ds_write2_b32 v44, v25, v26 offset0:32 offset1:98
	ds_write2_b32 v44, v27, v28 offset0:164 offset1:230
	ds_write2_b32 v45, v29, v30 offset0:40 offset1:106
	ds_write2_b32 v45, v31, v32 offset0:172 offset1:238
	ds_write2_b32 v46, v33, v34 offset0:48 offset1:114
	ds_write2_b32 v46, v35, v36 offset0:180 offset1:246
	ds_write2_b32 v47, v37, v38 offset0:56 offset1:122
	ds_write2_b32 v47, v39, v40 offset0:188 offset1:254
	s_waitcnt lgkmcnt(0)
	ds_read2_b32 v[14:15], v4 offset1:8
	ds_read2_b32 v[16:17], v4 offset0:33 offset1:41
	ds_read2_b32 v[18:19], v4 offset0:66 offset1:74
	ds_read2_b32 v[20:21], v4 offset0:99 offset1:107
	ds_read2_b32 v[22:23], v4 offset0:132 offset1:140
	s_waitcnt lgkmcnt(4)
	v_bfe_u32 v1, v14, 16, 1
	v_add3_u32 v1, v14, v1, s46
	s_waitcnt lgkmcnt(3)
	v_bfe_u32 v9, v16, 16, 1
	v_lshrrev_b32_e32 v1, 16, v1
	v_add3_u32 v9, v16, v9, s46
	ds_read2_b32 v[24:25], v4 offset0:165 offset1:173
	v_and_or_b32 v10, v9, s33, v1
	s_waitcnt lgkmcnt(3)
	v_bfe_u32 v1, v18, 16, 1
	v_add3_u32 v1, v18, v1, s46
	s_waitcnt lgkmcnt(2)
	v_bfe_u32 v9, v20, 16, 1
	ds_read2_b32 v[26:27], v4 offset0:198 offset1:206
	v_lshrrev_b32_e32 v1, 16, v1
	v_add3_u32 v9, v20, v9, s46
	ds_read2_b32 v[28:29], v4 offset0:231 offset1:239
	v_and_or_b32 v11, v9, s33, v1
	s_waitcnt lgkmcnt(3)
	v_bfe_u32 v1, v22, 16, 1
	v_add3_u32 v1, v22, v1, s46
	s_waitcnt lgkmcnt(2)
	v_bfe_u32 v9, v24, 16, 1
	v_lshrrev_b32_e32 v1, 16, v1
	v_add3_u32 v9, v24, v9, s46
	v_and_or_b32 v12, v9, s33, v1
	s_waitcnt lgkmcnt(1)
	v_bfe_u32 v1, v26, 16, 1
	v_add3_u32 v1, v26, v1, s46
	s_waitcnt lgkmcnt(0)
	v_bfe_u32 v9, v28, 16, 1
	v_lshrrev_b32_e32 v1, 16, v1
	v_add3_u32 v9, v28, v9, s46
	v_and_or_b32 v13, v9, s33, v1
	v_add_u32_e32 v1, s96, v3
	v_ashrrev_i32_e32 v9, 31, v1
	v_mul_lo_u32 v9, s82, v9
	v_mul_lo_u32 v14, s83, v1
	v_mad_u64_u32 v[30:31], s[4:5], s82, v1, 0
	v_add3_u32 v31, v31, v9, v14
	v_lshl_add_u64 v[30:31], v[30:31], 1, s[90:91]
	s_lshl_b64 s[4:5], s[52:53], 1
	v_lshl_add_u64 v[30:31], v[30:31], 0, s[4:5]
	v_mov_b32_e32 v1, v161
	v_lshl_add_u64 v[30:31], v[30:31], 0, v[0:1]
	v_bfe_u32 v9, v15, 16, 1
	global_store_dwordx4 v[30:31], v[10:13], off
	v_add3_u32 v9, v15, v9, s46
	v_lshrrev_b32_e32 v9, 16, v9
	v_bfe_u32 v10, v17, 16, 1
	v_add3_u32 v10, v17, v10, s46
	v_and_or_b32 v10, v10, s33, v9
	v_bfe_u32 v9, v19, 16, 1
	v_add3_u32 v9, v19, v9, s46
	v_bfe_u32 v11, v21, 16, 1
	v_lshrrev_b32_e32 v9, 16, v9
	v_add3_u32 v11, v21, v11, s46
	v_and_or_b32 v11, v11, s33, v9
	v_bfe_u32 v9, v23, 16, 1
	v_add3_u32 v9, v23, v9, s46
	v_bfe_u32 v12, v25, 16, 1
	v_lshrrev_b32_e32 v9, 16, v9
	v_add3_u32 v12, v25, v12, s46
	v_and_or_b32 v12, v12, s33, v9
	v_bfe_u32 v9, v27, 16, 1
	v_add3_u32 v9, v27, v9, s46
	v_bfe_u32 v13, v29, 16, 1
	v_lshrrev_b32_e32 v9, 16, v9
	v_add3_u32 v13, v29, v13, s46
	v_and_or_b32 v13, v13, s33, v9
	v_add_u32_e32 v9, s96, v5
	v_ashrrev_i32_e32 v14, 31, v9
	v_mul_lo_u32 v16, s82, v14
	v_mul_lo_u32 v17, s83, v9
	v_mad_u64_u32 v[14:15], s[28:29], s82, v9, 0
	v_add3_u32 v15, v15, v16, v17
	v_lshl_add_u64 v[14:15], v[14:15], 1, s[90:91]
	v_lshl_add_u64 v[14:15], v[14:15], 0, s[4:5]
	ds_read2_b32 v[16:17], v4 offset0:16 offset1:24
	v_lshl_add_u64 v[14:15], v[14:15], 0, v[0:1]
	global_store_dwordx4 v[14:15], v[10:13], off
	ds_read2_b32 v[14:15], v4 offset0:49 offset1:57
	ds_read2_b32 v[18:19], v4 offset0:82 offset1:90
	ds_read2_b32 v[20:21], v4 offset0:115 offset1:123
	s_waitcnt lgkmcnt(3)
	v_bfe_u32 v9, v16, 16, 1
	v_add3_u32 v9, v16, v9, s46
	s_waitcnt lgkmcnt(2)
	v_bfe_u32 v10, v14, 16, 1
	ds_read2_b32 v[22:23], v4 offset0:148 offset1:156
	v_lshrrev_b32_e32 v9, 16, v9
	v_add3_u32 v10, v14, v10, s46
	ds_read2_b32 v[24:25], v4 offset0:181 offset1:189
	v_and_or_b32 v10, v10, s33, v9
	s_waitcnt lgkmcnt(3)
	v_bfe_u32 v9, v18, 16, 1
	v_add3_u32 v9, v18, v9, s46
	s_waitcnt lgkmcnt(2)
	v_bfe_u32 v11, v20, 16, 1
	ds_read2_b32 v[26:27], v4 offset0:214 offset1:222
	v_lshrrev_b32_e32 v9, 16, v9
	v_add3_u32 v11, v20, v11, s46
	ds_read2_b32 v[28:29], v4 offset0:247 offset1:255
	v_and_or_b32 v11, v11, s33, v9
	s_waitcnt lgkmcnt(3)
	v_bfe_u32 v9, v22, 16, 1
	v_add3_u32 v9, v22, v9, s46
	s_waitcnt lgkmcnt(2)
	v_bfe_u32 v12, v24, 16, 1
	v_lshrrev_b32_e32 v9, 16, v9
	v_add3_u32 v12, v24, v12, s46
	v_and_or_b32 v12, v12, s33, v9
	s_waitcnt lgkmcnt(1)
	v_bfe_u32 v9, v26, 16, 1
	v_add3_u32 v9, v26, v9, s46
	s_waitcnt lgkmcnt(0)
	v_bfe_u32 v13, v28, 16, 1
	v_lshrrev_b32_e32 v9, 16, v9
	v_add3_u32 v13, v28, v13, s46
	v_and_or_b32 v13, v13, s33, v9
	v_add_u32_e32 v9, s96, v6
	v_ashrrev_i32_e32 v14, 31, v9
	v_mul_lo_u32 v14, s82, v14
	v_mul_lo_u32 v16, s83, v9
	v_mad_u64_u32 v[30:31], s[28:29], s82, v9, 0
	v_add3_u32 v31, v31, v14, v16
	v_lshl_add_u64 v[30:31], v[30:31], 1, s[90:91]
	v_lshl_add_u64 v[30:31], v[30:31], 0, s[4:5]
	v_lshl_add_u64 v[30:31], v[30:31], 0, v[0:1]
	v_bfe_u32 v9, v17, 16, 1
	global_store_dwordx4 v[30:31], v[10:13], off
	v_add3_u32 v9, v17, v9, s46
	v_lshrrev_b32_e32 v9, 16, v9
	v_bfe_u32 v10, v15, 16, 1
	v_add3_u32 v10, v15, v10, s46
	v_and_or_b32 v10, v10, s33, v9
	v_bfe_u32 v9, v19, 16, 1
	v_add3_u32 v9, v19, v9, s46
	v_bfe_u32 v11, v21, 16, 1
	v_lshrrev_b32_e32 v9, 16, v9
	v_add3_u32 v11, v21, v11, s46
	v_and_or_b32 v11, v11, s33, v9
	v_bfe_u32 v9, v23, 16, 1
	v_add3_u32 v9, v23, v9, s46
	v_bfe_u32 v12, v25, 16, 1
	v_lshrrev_b32_e32 v9, 16, v9
	v_add3_u32 v12, v25, v12, s46
	v_and_or_b32 v12, v12, s33, v9
	v_bfe_u32 v9, v27, 16, 1
	v_add3_u32 v9, v27, v9, s46
	v_bfe_u32 v13, v29, 16, 1
	v_lshrrev_b32_e32 v9, 16, v9
	v_add3_u32 v13, v29, v13, s46
	v_and_or_b32 v13, v13, s33, v9
	v_add_u32_e32 v9, s96, v7
	v_ashrrev_i32_e32 v14, 31, v9
	v_mul_lo_u32 v16, s82, v14
	v_mul_lo_u32 v17, s83, v9
	v_mad_u64_u32 v[14:15], s[28:29], s82, v9, 0
	v_add3_u32 v15, v15, v16, v17
	v_lshl_add_u64 v[14:15], v[14:15], 1, s[90:91]
	v_lshl_add_u64 v[14:15], v[14:15], 0, s[4:5]
	v_lshl_add_u64 v[14:15], v[14:15], 0, v[0:1]
	global_store_dwordx4 v[14:15], v[10:13], off
	s_waitcnt lgkmcnt(0)

; #define LAS __attribute__((address_space(3)))
; __device__ __forceinline__ unsigned pk2(float lo, float hi) { const f32x2 v = {lo, hi}; const bf16x2_cv b = __builtin_convertvector(v, bf16x2_cv); return __builtin_bit_cast(unsigned, b); }
; #define LAS __attribute__((address_space(3)))
; __device__ __forceinline__ unsigned pk2(float lo, float hi) { return f2bf(lo) | (f2bf(hi) << 16); }
; __device__ __forceinline__ void conv_store(const ConvItem& c, const float (&wv)[32], LAS float* scr, int lane) {
;     ...
;     for (int i = 0; i < 32; ++i) scr[(2 * i + (lane >> 5)) * 33 + (lane & 31)] = wv[i];
;     asm volatile("s_waitcnt lgkmcnt(0)" ::: "memory");
;     const int cc = lane & 7;
; #pragma unroll
;     for (int j = 0; j < 4; ++j) { const int n = (lane >> 3) + 8 * j; const LAS float* sp = scr + (8 * cc) * 33 + n;
;         v4u o; o.x = pk2(sp[0 * 33], sp[1 * 33]); o.y = pk2(sp[2 * 33], sp[3 * 33]); o.z = pk2(sp[4 * 33], sp[5 * 33]); o.w = pk2(sp[6 * 33], sp[7 * 33]);
;         *(v4u*)(c.WT + (size_t)(r0 + n) * c.K + k0 + 8 * cc) = o; }
;     asm volatile("s_waitcnt lgkmcnt(0)" ::: "memory");
.LBB0_930:
	s_waitcnt vmcnt(32)
	ds_write2_b32 v8, v1, v41 offset1:66
	ds_write2_b32 v8, v42, v44 offset0:132 offset1:198
	v_add_u32_e32 v41, 0x400, v8
	ds_write2_b32 v41, v43, v45 offset0:8 offset1:74
	ds_write2_b32 v41, v46, v47 offset0:140 offset1:206
	v_add_u32_e32 v42, 0x800, v8
	v_add_u32_e32 v43, 0xc00, v8
	v_add_u32_e32 v44, 0x1000, v8
	v_add_u32_e32 v45, 0x1400, v8
	v_add_u32_e32 v46, 0x1800, v8
	v_add_u32_e32 v47, 0x1c00, v8
	ds_write2_b32 v42, v48, v49 offset0:16 offset1:82
	ds_write2_b32 v42, v50, v51 offset0:148 offset1:214
	ds_write2_b32 v43, v52, v53 offset0:24 offset1:90
	ds_write2_b32 v43, v54, v55 offset0:156 offset1:222
	ds_write2_b32 v44, v56, v57 offset0:32 offset1:98
	ds_write2_b32 v44, v58, v59 offset0:164 offset1:230
	ds_write2_b32 v45, v60, v61 offset0:40 offset1:106
	ds_write2_b32 v45, v62, v63 offset0:172 offset1:238
	ds_write2_b32 v46, v64, v65 offset0:48 offset1:114
	ds_write2_b32 v46, v66, v67 offset0:180 offset1:246
	ds_write2_b32 v47, v68, v69 offset0:56 offset1:122
	ds_write2_b32 v47, v70, v71 offset0:188 offset1:254
	s_waitcnt lgkmcnt(0)
	ds_read2_b32 v[52:53], v4 offset1:8
	ds_read2_b32 v[54:55], v4 offset0:33 offset1:41
	ds_read2_b32 v[56:57], v4 offset0:66 offset1:74
	ds_read2_b32 v[58:59], v4 offset0:99 offset1:107
	ds_read2_b32 v[60:61], v4 offset0:132 offset1:140
	s_waitcnt lgkmcnt(4)
	v_bfe_u32 v1, v52, 16, 1
	v_add3_u32 v1, v52, v1, s46
	s_waitcnt lgkmcnt(3)
	v_bfe_u32 v48, v54, 16, 1
	v_lshrrev_b32_e32 v1, 16, v1
	v_add3_u32 v48, v54, v48, s46
	ds_read2_b32 v[62:63], v4 offset0:165 offset1:173
	v_and_or_b32 v48, v48, s33, v1
	s_waitcnt lgkmcnt(3)
	v_bfe_u32 v1, v56, 16, 1
	v_add3_u32 v1, v56, v1, s46
	s_waitcnt lgkmcnt(2)
	v_bfe_u32 v49, v58, 16, 1
	ds_read2_b32 v[64:65], v4 offset0:198 offset1:206
	v_lshrrev_b32_e32 v1, 16, v1
	v_add3_u32 v49, v58, v49, s46
	ds_read2_b32 v[66:67], v4 offset0:231 offset1:239
	v_and_or_b32 v49, v49, s33, v1
	s_waitcnt lgkmcnt(3)
	v_bfe_u32 v1, v60, 16, 1
	v_add3_u32 v1, v60, v1, s46
	s_waitcnt lgkmcnt(2)
	v_bfe_u32 v50, v62, 16, 1
	v_lshrrev_b32_e32 v1, 16, v1
	v_add3_u32 v50, v62, v50, s46
	v_and_or_b32 v50, v50, s33, v1
	s_waitcnt lgkmcnt(1)
	v_bfe_u32 v1, v64, 16, 1
	v_add3_u32 v1, v64, v1, s46
	s_waitcnt lgkmcnt(0)
	v_bfe_u32 v51, v66, 16, 1
	v_lshrrev_b32_e32 v1, 16, v1
	v_add3_u32 v51, v66, v51, s46
	v_and_or_b32 v51, v51, s33, v1
	v_add_u32_e32 v1, s4, v3
	v_ashrrev_i32_e32 v52, 31, v1
	v_mul_lo_u32 v52, s86, v52
	v_mul_lo_u32 v54, s87, v1
	v_mad_u64_u32 v[68:69], s[28:29], s86, v1, 0
	v_add3_u32 v69, v69, v52, v54
	v_lshl_add_u64 v[68:69], v[68:69], 1, s[88:89]
	s_lshl_b64 s[56:57], s[58:59], 1
	v_lshl_add_u64 v[68:69], v[68:69], 0, s[56:57]
	v_mov_b32_e32 v1, v161
	v_lshl_add_u64 v[68:69], v[68:69], 0, v[0:1]
	global_store_dwordx4 v[68:69], v[48:51], off
	v_bfe_u32 v52, v67, 16, 1
	v_add3_u32 v52, v67, v52, s46
	v_bfe_u32 v48, v53, 16, 1
	v_add3_u32 v48, v53, v48, s46
	v_bfe_u32 v49, v55, 16, 1
	v_lshrrev_b32_e32 v48, 16, v48
	v_add3_u32 v49, v55, v49, s46
	v_and_or_b32 v48, v49, s33, v48
	v_bfe_u32 v49, v57, 16, 1
	v_add3_u32 v49, v57, v49, s46
	v_bfe_u32 v50, v59, 16, 1
	v_lshrrev_b32_e32 v49, 16, v49
	v_add3_u32 v50, v59, v50, s46
	v_and_or_b32 v49, v50, s33, v49
	v_bfe_u32 v50, v61, 16, 1
	v_add3_u32 v50, v61, v50, s46
	v_bfe_u32 v51, v63, 16, 1
	v_lshrrev_b32_e32 v50, 16, v50
	v_add3_u32 v51, v63, v51, s46
	v_and_or_b32 v50, v51, s33, v50
	v_bfe_u32 v51, v65, 16, 1
	v_add3_u32 v51, v65, v51, s46
	v_lshrrev_b32_e32 v51, 16, v51
	v_and_or_b32 v51, v52, s33, v51
	v_add_u32_e32 v52, s4, v5
	v_ashrrev_i32_e32 v53, 31, v52
	v_mul_lo_u32 v54, s86, v53
	v_mul_lo_u32 v55, s87, v52
	v_mad_u64_u32 v[52:53], s[28:29], s86, v52, 0
	v_add3_u32 v53, v53, v54, v55
	v_lshl_add_u64 v[52:53], v[52:53], 1, s[88:89]
	v_lshl_add_u64 v[52:53], v[52:53], 0, s[56:57]
	ds_read2_b32 v[54:55], v4 offset0:16 offset1:24
	v_lshl_add_u64 v[52:53], v[52:53], 0, v[0:1]
	global_store_dwordx4 v[52:53], v[48:51], off
	ds_read2_b32 v[52:53], v4 offset0:49 offset1:57
	ds_read2_b32 v[56:57], v4 offset0:82 offset1:90
	ds_read2_b32 v[58:59], v4 offset0:115 offset1:123
	s_waitcnt lgkmcnt(3)
	v_bfe_u32 v48, v54, 16, 1
	v_add3_u32 v48, v54, v48, s46
	s_waitcnt lgkmcnt(2)
	v_bfe_u32 v49, v52, 16, 1
	ds_read2_b32 v[60:61], v4 offset0:148 offset1:156
	v_lshrrev_b32_e32 v48, 16, v48
	v_add3_u32 v49, v52, v49, s46
	ds_read2_b32 v[62:63], v4 offset0:181 offset1:189
	v_and_or_b32 v48, v49, s33, v48
	s_waitcnt lgkmcnt(3)
	v_bfe_u32 v49, v56, 16, 1
	v_add3_u32 v49, v56, v49, s46
	s_waitcnt lgkmcnt(2)
	v_bfe_u32 v50, v58, 16, 1
	ds_read2_b32 v[64:65], v4 offset0:214 offset1:222
	v_lshrrev_b32_e32 v49, 16, v49
	v_add3_u32 v50, v58, v50, s46
	ds_read2_b32 v[66:67], v4 offset0:247 offset1:255
	v_and_or_b32 v49, v50, s33, v49
	s_waitcnt lgkmcnt(3)
	v_bfe_u32 v50, v60, 16, 1
	v_add3_u32 v50, v60, v50, s46
	s_waitcnt lgkmcnt(2)
	v_bfe_u32 v51, v62, 16, 1
	v_lshrrev_b32_e32 v50, 16, v50
	v_add3_u32 v51, v62, v51, s46
	v_and_or_b32 v50, v51, s33, v50
	s_waitcnt lgkmcnt(1)
	v_bfe_u32 v51, v64, 16, 1
	v_add3_u32 v51, v64, v51, s46
	s_waitcnt lgkmcnt(0)
	v_bfe_u32 v52, v66, 16, 1
	v_lshrrev_b32_e32 v51, 16, v51
	v_add3_u32 v52, v66, v52, s46
	v_and_or_b32 v51, v52, s33, v51
	v_add_u32_e32 v52, s4, v6
	v_ashrrev_i32_e32 v54, 31, v52
	v_mul_lo_u32 v54, s86, v54
	v_mul_lo_u32 v56, s87, v52
	v_mad_u64_u32 v[68:69], s[28:29], s86, v52, 0
	v_add3_u32 v69, v69, v54, v56
	v_lshl_add_u64 v[68:69], v[68:69], 1, s[88:89]
	v_lshl_add_u64 v[68:69], v[68:69], 0, s[56:57]
	v_lshl_add_u64 v[68:69], v[68:69], 0, v[0:1]
	global_store_dwordx4 v[68:69], v[48:51], off
	v_bfe_u32 v52, v67, 16, 1
	v_add3_u32 v52, v67, v52, s46
	v_bfe_u32 v48, v55, 16, 1
	v_add3_u32 v48, v55, v48, s46
	v_bfe_u32 v49, v53, 16, 1
	v_lshrrev_b32_e32 v48, 16, v48
	v_add3_u32 v49, v53, v49, s46
	v_and_or_b32 v48, v49, s33, v48
	v_bfe_u32 v49, v57, 16, 1
	v_add3_u32 v49, v57, v49, s46
	v_bfe_u32 v50, v59, 16, 1
	v_lshrrev_b32_e32 v49, 16, v49
	v_add3_u32 v50, v59, v50, s46
	v_and_or_b32 v49, v50, s33, v49
	v_bfe_u32 v50, v61, 16, 1
	v_add3_u32 v50, v61, v50, s46
	v_bfe_u32 v51, v63, 16, 1
	v_lshrrev_b32_e32 v50, 16, v50
	v_add3_u32 v51, v63, v51, s46
	v_and_or_b32 v50, v51, s33, v50
	v_bfe_u32 v51, v65, 16, 1
	v_add3_u32 v51, v65, v51, s46
	v_lshrrev_b32_e32 v51, 16, v51
	v_and_or_b32 v51, v52, s33, v51
	v_add_u32_e32 v52, s4, v7
	v_ashrrev_i32_e32 v53, 31, v52
	v_mul_lo_u32 v54, s86, v53
	v_mul_lo_u32 v55, s87, v52
	v_mad_u64_u32 v[52:53], s[28:29], s86, v52, 0
	v_add3_u32 v53, v53, v54, v55
	v_lshl_add_u64 v[52:53], v[52:53], 1, s[88:89]
	v_lshl_add_u64 v[52:53], v[52:53], 0, s[56:57]
	v_lshl_add_u64 v[52:53], v[52:53], 0, v[0:1]
	global_store_dwordx4 v[52:53], v[48:51], off
	s_waitcnt lgkmcnt(0)
	s_andn2_b64 vcc, exec, s[92:93]
	s_cbranch_vccnz .Lc0_drain
; __device__ __forceinline__ void conv_store(const ConvItem& c, const float (&wv)[32], LAS float* scr, int lane) {
;     const int nblk = c.N / 32, kb = c.item / nblk, nb = c.item % nblk, k0 = 64 * kb, n0 = 32 * nb;
;     int r0 = n0;
;     if (c.gu) { const int up = n0 >= DFF ? 1 : 0, nn = n0 - up * DFF; r0 = (nn >> 7) * 256 + up * 128 + (nn & 127); }
	s_xor_b64 s[28:29], s[84:85], -1
	s_andn2_b64 vcc, exec, s[28:29]
	s_cbranch_vccnz .LBB0_874
	s_cmpk_gt_i32 s5, 0xaf
	s_cselect_b32 s4, 0xffffea00, 0
	s_cselect_b32 s5, 0x80, 0
	s_add_i32 s4, s4, s96
	s_lshl_b32 s4, s4, 1
	s_and_b32 s24, s96, 0x60
	s_and_b32 s4, s4, 0xffffff00
	s_or_b32 s5, s24, s5
	s_or_b32 s96, s5, s4
	s_branch .LBB0_874
